# c21a + back-edge rotation (loop-back barrier becomes loop head) in MLA and DIFF tile loops + DIFF row-sum chain started in the K-prime MFMA gap
# speedup vs baseline: 1.0066x; 1.0027x over previous
.LBB0_871:
	s_barrier
	s_add_i32 s80, s75, -3
	s_lshl_b32 s76, s74, 14
	s_add_i32 s8, s69, s76
	v_lshl_add_u64 v[2:3], v[226:227], 0, s[34:35]
	s_mov_b32 m0, s8
	s_nop 0
	global_load_lds_dwordx4 v[2:3], off
	s_add_i32 m0, s8, 0x2000
	s_mul_i32 s8, s60, 0x6300
	s_add_i32 s61, s68, s8
	global_load_lds_dwordx4 v[226:227], off
	s_add_i32 m0, s61, 0xc000
	s_add_i32 s8, s75, -1
	s_cmp_lt_u32 s8, s77
	s_cselect_b32 s8, s8, s73
	s_lshl_b32 s8, s8, 6
	s_lshl_b64 s[58:59], s[8:9], 12
	v_lshl_add_u64 v[2:3], v[218:219], 0, s[58:59]
	global_load_lds_dwordx4 v[2:3], off
	v_lshl_add_u64 v[2:3], v[2:3], 0, s[12:13]
	s_add_i32 m0, s61, 0xe100
	s_lshl_b64 s[82:83], s[8:9], 7
	global_load_lds_dwordx4 v[2:3], off
	v_lshl_add_u64 v[2:3], v[224:225], 0, s[82:83]
	s_add_i32 m0, s61, 0x10200
	s_nop 0
	global_load_lds_dwordx4 v[2:3], off
	s_mul_i32 s8, s79, 0x6300
	s_add_i32 s8, s8, 0
	v_add_u32_e32 v0, s8, v237
	ds_read_b128 v[2:5], v0 offset:49152
	ds_read_b128 v[6:9], v0 offset:50176
	s_waitcnt lgkmcnt(0)
	v_mfma_f32_32x32x16_bf16 v[112:127], v[2:5], v[188:191], 0
	v_mfma_f32_32x32x16_bf16 v[128:143], v[6:9], v[188:191], 0
	ds_read_b128 v[2:5], v0 offset:51264
	ds_read_b128 v[6:9], v0 offset:52288
	s_waitcnt lgkmcnt(0)
	v_mfma_f32_32x32x16_bf16 v[112:127], v[2:5], v[184:187], v[112:127]
	v_mfma_f32_32x32x16_bf16 v[128:143], v[6:9], v[184:187], v[128:143]
	ds_read_b128 v[2:5], v0 offset:53376
	ds_read_b128 v[6:9], v0 offset:54400
	s_waitcnt lgkmcnt(0)
	v_mfma_f32_32x32x16_bf16 v[112:127], v[2:5], v[180:183], v[112:127]
	v_mfma_f32_32x32x16_bf16 v[128:143], v[6:9], v[180:183], v[128:143]
	ds_read_b128 v[2:5], v0 offset:55488
	ds_read_b128 v[6:9], v0 offset:56512
	s_waitcnt lgkmcnt(0)
	v_mfma_f32_32x32x16_bf16 v[112:127], v[2:5], v[176:179], v[112:127]
	v_mfma_f32_32x32x16_bf16 v[128:143], v[6:9], v[176:179], v[128:143]
	ds_read_b128 v[2:5], v0 offset:57600
	ds_read_b128 v[6:9], v0 offset:58624
	s_waitcnt lgkmcnt(0)
	v_mfma_f32_32x32x16_bf16 v[112:127], v[2:5], v[172:175], v[112:127]
	v_mfma_f32_32x32x16_bf16 v[128:143], v[6:9], v[172:175], v[128:143]
	ds_read_b128 v[2:5], v0 offset:59712
	ds_read_b128 v[6:9], v0 offset:60736
	s_waitcnt lgkmcnt(0)
	v_mfma_f32_32x32x16_bf16 v[112:127], v[2:5], v[168:171], v[112:127]
	v_mfma_f32_32x32x16_bf16 v[128:143], v[6:9], v[168:171], v[128:143]
	ds_read_b128 v[2:5], v0 offset:61824
	ds_read_b128 v[6:9], v0 offset:62848
	s_waitcnt lgkmcnt(0)
	v_mfma_f32_32x32x16_bf16 v[112:127], v[2:5], v[164:167], v[112:127]
	v_mfma_f32_32x32x16_bf16 v[128:143], v[6:9], v[164:167], v[128:143]
	ds_read_b128 v[2:5], v0 offset:63936
	ds_read_b128 v[6:9], v0 offset:64960
	v_add_u32_e32 v0, 0xc000, v0
	s_waitcnt lgkmcnt(0)
	v_mfma_f32_32x32x16_bf16 v[112:127], v[2:5], v[160:163], v[112:127]
	ds_read_b128 v[2:5], v0 offset:17920
	ds_read_b128 v[10:13], v0 offset:16896
	v_mfma_f32_32x32x16_bf16 v[128:143], v[6:9], v[160:163], v[128:143]
	ds_read_b128 v[6:9], v0 offset:20032
	ds_read_b128 v[192:195], v0 offset:19008
	ds_read_b128 v[196:199], v0 offset:22144
	ds_read_b128 v[200:203], v0 offset:21120
	ds_read_b128 v[204:207], v0 offset:24256
	ds_read_b128 v[208:211], v0 offset:23232
	v_add_f32_e32 v0, 0, v96
	v_add_f32_e32 v0, v97, v0
	v_add_f32_e32 v0, v98, v0
	v_add_f32_e32 v0, v99, v0
	v_add_f32_e32 v0, v100, v0
	v_add_f32_e32 v0, v101, v0
	s_waitcnt lgkmcnt(0)
	v_mfma_f32_32x32x16_bf16 v[112:127], v[10:13], v[156:159], v[112:127]
	v_add_f32_e32 v0, v102, v0
	v_add_f32_e32 v0, v103, v0
	v_add_f32_e32 v0, v104, v0
	v_add_f32_e32 v0, v105, v0
	v_add_f32_e32 v0, v106, v0
	v_add_f32_e32 v0, v107, v0
	v_add_f32_e32 v0, v108, v0
	v_mfma_f32_32x32x16_bf16 v[128:143], v[2:5], v[156:159], v[128:143]
	v_add_f32_e32 v0, v109, v0
	v_add_f32_e32 v0, v110, v0
	v_add_f32_e32 v0, v111, v0
	v_add_f32_e32 v0, v80, v0
	v_add_f32_e32 v0, v81, v0
	v_add_f32_e32 v0, v82, v0
	v_add_f32_e32 v0, v83, v0
	v_mfma_f32_32x32x16_bf16 v[112:127], v[192:195], v[152:155], v[112:127]
	v_add_f32_e32 v0, v84, v0
	v_add_f32_e32 v0, v85, v0
	v_add_f32_e32 v0, v86, v0
	v_add_f32_e32 v0, v87, v0
	v_add_f32_e32 v0, v88, v0
	v_add_f32_e32 v0, v89, v0
	v_add_f32_e32 v0, v90, v0
	v_mfma_f32_32x32x16_bf16 v[128:143], v[6:9], v[152:155], v[128:143]
	v_add_f32_e32 v0, v91, v0
	v_add_f32_e32 v0, v92, v0
	v_add_f32_e32 v0, v93, v0
	v_add_f32_e32 v0, v94, v0
	v_add_f32_e32 v14, v95, v0
	v_mov_b32_e32 v15, v14
	s_nop 1
	v_permlane32_swap_b32_e32 v14, v15
	v_mfma_f32_32x32x16_bf16 v[112:127], v[200:203], v[148:151], v[112:127]
	v_cvt_pk_bf16_f32 v192, v96, v97
	v_cvt_pk_bf16_f32 v193, v98, v99
	v_cvt_pk_bf16_f32 v194, v100, v101
	v_cvt_pk_bf16_f32 v195, v102, v103
	v_cvt_pk_bf16_f32 v10, v104, v105
	v_cvt_pk_bf16_f32 v11, v106, v107
	v_cvt_pk_bf16_f32 v12, v108, v109
	v_mfma_f32_32x32x16_bf16 v[128:143], v[196:199], v[148:151], v[128:143]
	v_cvt_pk_bf16_f32 v13, v110, v111
	v_cvt_pk_bf16_f32 v6, v80, v81
	v_cvt_pk_bf16_f32 v7, v82, v83
	v_cvt_pk_bf16_f32 v8, v84, v85
	v_cvt_pk_bf16_f32 v9, v86, v87
	v_cvt_pk_bf16_f32 v2, v88, v89
	v_cvt_pk_bf16_f32 v3, v90, v91
	v_mfma_f32_32x32x16_bf16 v[112:127], v[208:211], v[144:147], v[112:127]
	v_cvt_pk_bf16_f32 v4, v92, v93
	v_cvt_pk_bf16_f32 v5, v94, v95
	v_mfma_f32_32x32x16_bf16 v[128:143], v[204:207], v[144:147], v[128:143]
	s_cmp_gt_i32 s80, s72
	s_cbranch_scc1 .Lold_mla_odd
	v_lshl_add_u32 v0, s60, 14, v235
	ds_read_b64_tr_b16 v[208:209], v0 offset:0
	ds_read_b64_tr_b16 v[210:211], v0 offset:0x800
	ds_read_b64_tr_b16 v[204:205], v0 offset:0x1000
	ds_read_b64_tr_b16 v[206:207], v0 offset:0x1800
	ds_read_b64_tr_b16 v[200:201], v0 offset:0x2000
	ds_read_b64_tr_b16 v[202:203], v0 offset:0x2800
	ds_read_b64_tr_b16 v[196:197], v0 offset:0x3000
	ds_read_b64_tr_b16 v[198:199], v0 offset:0x3800
	s_nop 1
	v_max3_f32 v245, v112, v113, v114
	v_max3_f32 v246, v128, v129, v130
	v_max3_f32 v245, v245, v115, v116
	v_max3_f32 v246, v246, v131, v132
	v_max3_f32 v245, v245, v117, v118
	v_max3_f32 v246, v246, v133, v134
	v_max3_f32 v245, v245, v119, v120
	v_max3_f32 v246, v246, v135, v136
	v_max3_f32 v245, v245, v121, v122
	v_max3_f32 v246, v246, v137, v138
	v_max3_f32 v245, v245, v123, v124
	v_max3_f32 v246, v246, v139, v140
	v_max3_f32 v245, v245, v125, v126
	v_max3_f32 v246, v246, v141, v142
	v_max_f32_e32 v245, v245, v127
	v_max_f32_e32 v246, v246, v143
	v_max_f32_e32 v245, v245, v246
	v_mov_b32_e32 v246, v245
	s_nop 1
	v_permlane32_swap_b32_e32 v245, v246
	v_max_f32_e32 v245, v245, v246
	v_sub_f32_e32 v246, v245, v236
	v_cmp_ge_f32_e32 vcc, s29, v246
	s_cmp_eq_u64 vcc, exec
	v_mov_b32_e32 v240, 1.0
	s_cbranch_scc0 .Lfm_odd_ev

.LBB0_881:
	v_add_f32_e32 v2, v14, v15
	s_waitcnt vmcnt(0)
	s_add_i32 s8, s81, 1
	v_fmac_f32_e32 v2, v239, v234
	v_add_f32_e32 v234, v241, v242
	s_cmp_lg_u32 s81, 2
	v_fmac_f32_e32 v234, v2, v240
	s_cselect_b32 s8, s8, 0
	v_lshl_add_u64 v[226:227], v[226:227], 0, s[10:11]
	s_add_i32 s75, s75, 2
	s_and_b64 vcc, exec, s[58:59]
	s_waitcnt vmcnt(0)
	s_cbranch_vccnz .Lrot5_exit
	s_mov_b32 s60, s74
	s_mov_b32 s79, s81
	s_mov_b32 s74, s8
	v_mov_b32_e32 v239, v0
	s_branch .LBB0_871
.Lrot5_exit:
	s_barrier
	s_branch .LBB0_885

.LBB0_1422:
	s_barrier
	s_lshl_b32 s18, s44, 14
	s_add_i32 s52, s81, s18
	s_mov_b32 m0, s52
	v_lshl_add_u64 v[0:1], v[194:195], 0, s[14:15]
	global_load_lds_dwordx4 v[194:195], off
	s_add_i32 m0, s52, 0x2000
	s_mul_i32 s52, s54, 0x2100
	s_add_i32 s52, s22, s52
	global_load_lds_dwordx4 v[0:1], off
	s_add_i32 m0, s52, 0xc000
	s_add_i32 s52, s45, -1
	s_cmp_lt_u32 s52, s2
	s_cselect_b32 s55, s52, s3
	s_lshl_b32 s56, s55, 6
	v_mad_u64_u32 v[0:1], s[52:53], s56, v209, v[192:193]
	v_lshl_add_u64 v[0:1], v[0:1], 0, s[10:11]
	global_load_lds_dwordx4 v[0:1], off
	s_mul_i32 s52, s55, 0x60000
	s_mul_hi_u32 s53, s56, 0x1800
	s_mul_i32 s55, s69, 0x2100
	s_add_i32 s71, s55, 0
	s_sub_i32 s55, s65, 64
	v_cvt_f32_u32_e32 v0, s55
	v_add_u32_e32 v166, s71, v220
	v_add_u32_e32 v167, s71, v217
	ds_read_b128 v[4:7], v166 offset:49152
	ds_read_b128 v[8:11], v167 offset:49152
	v_sub_f32_e32 v196, v0, v161
	v_fma_f32 v0, v210, v196, -v221
	v_cvt_pk_bf16_f32 v1, v0, v3
	v_lshlrev_b32_e32 v1, 16, v1
	v_sub_f32_e32 v0, v0, v1
	v_cvt_pk_bf16_f32 v2, v0, v3
	v_lshlrev_b32_e32 v2, 16, v2
	v_sub_f32_e32 v0, v0, v2
	v_cvt_pk_bf16_f32 v1, v1, v2
	v_cvt_pk_bf16_f32 v0, v0, v3
	s_nop 0
	v_cndmask_b32_e64 v2, 0, v0, s[4:5]
	v_cndmask_b32_e64 v0, 0, v160, s[4:5]
	v_cndmask_b32_e64 v1, 0, v1, s[4:5]
	s_nop 1
	v_mfma_f32_32x32x16_bf16 v[128:143], v[248:251], v[0:3], 0
	v_add_f32_e32 v226, v96, v97
	v_add_f32_e32 v226, v98, v226
	v_add_f32_e32 v226, v99, v226
	v_add_f32_e32 v226, v100, v226
	v_mfma_f32_32x32x16_bf16 v[112:127], v[252:255], v[0:3], 0
	v_add_f32_e32 v1, v101, v226
	v_add_f32_e32 v1, v102, v1
	s_waitcnt lgkmcnt(0)
	v_mfma_f32_32x32x16_bf16 v[128:143], v[8:11], v[156:159], v[128:143]
	v_add_f32_e32 v1, v103, v1
	v_add_f32_e32 v1, v104, v1
	v_add_f32_e32 v1, v105, v1
	v_add_f32_e32 v1, v106, v1
	v_add_f32_e32 v1, v107, v1
	v_add_f32_e32 v1, v108, v1
	v_add_f32_e32 v1, v109, v1
	v_mfma_f32_32x32x16_bf16 v[112:127], v[4:7], v[156:159], v[112:127]
	ds_read_b128 v[4:7], v166 offset:51264
	ds_read_b128 v[8:11], v167 offset:51264
	v_add_f32_e32 v1, v110, v1
	v_add_f32_e32 v1, v111, v1
	v_add_f32_e32 v1, v80, v1
	v_add_f32_e32 v1, v81, v1
	v_add_f32_e32 v1, v82, v1
	v_add_f32_e32 v1, v83, v1
	s_waitcnt lgkmcnt(0)
	v_mfma_f32_32x32x16_bf16 v[128:143], v[8:11], v[152:155], v[128:143]
	v_add_f32_e32 v1, v84, v1
	v_add_f32_e32 v1, v85, v1
	v_add_f32_e32 v1, v86, v1
	v_add_f32_e32 v1, v87, v1
	v_add_f32_e32 v1, v88, v1
	v_add_f32_e32 v1, v89, v1
	v_add_f32_e32 v1, v90, v1
	v_mfma_f32_32x32x16_bf16 v[112:127], v[4:7], v[152:155], v[112:127]
	ds_read_b128 v[4:7], v166 offset:53376
	ds_read_b128 v[8:11], v167 offset:53376
	v_add_f32_e32 v1, v91, v1
	v_add_f32_e32 v1, v92, v1
	v_add_f32_e32 v1, v93, v1
	v_add_f32_e32 v1, v94, v1
	v_add_f32_e32 v223, v95, v1
	v_mov_b32_e32 v224, v223
	s_waitcnt lgkmcnt(0)
	v_mfma_f32_32x32x16_bf16 v[128:143], v[8:11], v[148:151], v[128:143]
	v_permlane32_swap_b32_e32 v223, v224
	v_mfma_f32_32x32x16_bf16 v[112:127], v[4:7], v[148:151], v[112:127]
	ds_read_b128 v[4:7], v166 offset:55488
	ds_read_b128 v[8:11], v167 offset:55488
	v_cvt_pk_bf16_f32 v166, v96, v97
	v_cvt_pk_bf16_f32 v167, v98, v99
	v_cvt_pk_bf16_f32 v168, v100, v101
	v_cvt_pk_bf16_f32 v169, v102, v103
	v_cvt_pk_bf16_f32 v12, v104, v105
	v_cvt_pk_bf16_f32 v13, v106, v107
	s_waitcnt lgkmcnt(0)
	v_mfma_f32_32x32x16_bf16 v[128:143], v[8:11], v[144:147], v[128:143]
	v_cvt_pk_bf16_f32 v14, v108, v109
	v_cvt_pk_bf16_f32 v15, v110, v111
	v_cvt_pk_bf16_f32 v8, v80, v81
	v_cvt_pk_bf16_f32 v9, v82, v83
	v_cvt_pk_bf16_f32 v10, v84, v85
	v_cvt_pk_bf16_f32 v11, v86, v87
	v_mfma_f32_32x32x16_bf16 v[112:127], v[4:7], v[144:147], v[112:127]
	v_cvt_pk_bf16_f32 v4, v88, v89
	v_cvt_pk_bf16_f32 v5, v90, v91
	v_cvt_pk_bf16_f32 v6, v92, v93
	v_cvt_pk_bf16_f32 v7, v94, v95
	v_lshl_add_u32 v1, s54, 14, v215
	ds_read_b64_tr_b16 v[182:183], v1 offset:0
	ds_read_b64_tr_b16 v[184:185], v1 offset:0x800
	ds_read_b64_tr_b16 v[178:179], v1 offset:0x1000
	ds_read_b64_tr_b16 v[180:181], v1 offset:0x1800
	s_add_i32 s70, s45, -3
	s_add_i32 s54, s19, s45
	ds_read_b64_tr_b16 v[174:175], v1 offset:0x2000
	s_cmp_eq_u32 s54, 3
	ds_read_b64_tr_b16 v[176:177], v1 offset:0x2800
	s_cselect_b64 s[54:55], -1, 0
	ds_read_b64_tr_b16 v[170:171], v1 offset:0x3000
	v_cndmask_b32_e64 v2, 0, 1, s[54:55]
	ds_read_b64_tr_b16 v[172:173], v1 offset:0x3800
	s_cmp_lt_i32 s70, s31
	s_cbranch_scc0 .Lold_odd
	v_max3_f32 v245, v128, v129, v130
	v_max3_f32 v246, v112, v113, v114
	v_max3_f32 v245, v245, v131, v132
	v_max3_f32 v246, v246, v115, v116
	v_max3_f32 v245, v245, v133, v134
	v_max3_f32 v246, v246, v117, v118
	v_max3_f32 v245, v245, v135, v136
	v_max3_f32 v246, v246, v119, v120
	v_max3_f32 v245, v245, v137, v138
	v_max3_f32 v246, v246, v121, v122
	v_max3_f32 v245, v245, v139, v140
	v_max3_f32 v246, v246, v123, v124
	v_max3_f32 v245, v245, v141, v142
	v_max3_f32 v246, v246, v125, v126
	v_max_f32_e32 v245, v245, v143
	v_max_f32_e32 v246, v246, v127
	v_max_f32_e32 v245, v245, v246
	v_mov_b32_e32 v246, v245
	s_nop 1
	v_permlane32_swap_b32_e32 v245, v246
	v_max_f32_e32 v245, v245, v246
	v_cmp_ge_f32_e32 vcc, s68, v245
	s_cmp_eq_u64 vcc, exec
	v_mov_b32_e32 v225, 1.0
	s_cbranch_scc0 .Lf_odd_resc

.LBB0_1437:
	s_waitcnt vmcnt(0)
	s_add_i32 s54, s44, 1
	s_cmp_lg_u32 s44, 2
	s_cselect_b32 s67, s54, 0
	s_waitcnt vmcnt(0)
	s_barrier
	s_lshl_b32 s66, s67, 14
	s_add_i32 s54, s81, s66
	v_lshl_add_u64 v[4:5], v[190:191], 0, s[52:53]
	s_mov_b32 m0, s54
	s_add_i32 s52, s71, s82
	global_load_lds_dwordx4 v[4:5], off
	v_lshl_add_u64 v[4:5], v[4:5], 0, s[14:15]
	s_add_i32 m0, s54, 0x2000
	s_add_i32 s52, s52, s27
	global_load_lds_dwordx4 v[4:5], off
	s_add_i32 m0, s52, 0xc000
	s_cmp_ge_u32 s45, s2
	s_cselect_b64 s[52:53], -1, 0
	s_cmp_lt_u32 s45, s2
	s_cselect_b32 s54, s45, s3
	s_lshl_b32 s54, s54, 6
	v_mad_u64_u32 v[4:5], s[54:55], s54, v209, v[192:193]
	v_lshl_add_u64 v[4:5], v[4:5], 0, s[10:11]
	global_load_lds_dwordx4 v[4:5], off
	v_cvt_f32_u32_e32 v1, s65
	s_mul_i32 s54, s44, 0x2100
	s_add_i32 s54, s54, 0
	v_add_u32_e32 v166, s54, v220
	v_sub_f32_e32 v196, v1, v161
	v_add_u32_e32 v167, s54, v217
	v_fma_f32 v1, v210, v196, -v221
	ds_read_b128 v[4:7], v166 offset:49152
	ds_read_b128 v[8:11], v167 offset:49152
	v_cvt_pk_bf16_f32 v2, v1, v3
	v_lshlrev_b32_e32 v2, 16, v2
	v_sub_f32_e32 v1, v1, v2
	v_cvt_pk_bf16_f32 v12, v1, v3
	v_lshlrev_b32_e32 v12, 16, v12
	v_sub_f32_e32 v1, v1, v12
	v_cvt_pk_bf16_f32 v12, v2, v12
	v_cvt_pk_bf16_f32 v1, v1, v3
	s_nop 0
	v_cndmask_b32_e64 v2, 0, v1, s[4:5]
	v_cndmask_b32_e64 v1, 0, v12, s[4:5]
	s_nop 1
	v_mfma_f32_32x32x16_bf16 v[128:143], v[248:251], v[0:3], 0
	v_add_f32_e32 v226, v96, v97
	v_add_f32_e32 v226, v98, v226
	v_add_f32_e32 v226, v99, v226
	v_add_f32_e32 v226, v100, v226
	s_nop 0
	v_mfma_f32_32x32x16_bf16 v[112:127], v[252:255], v[0:3], 0
	v_add_f32_e32 v1, v101, v226
	v_add_f32_e32 v1, v102, v1
	s_waitcnt lgkmcnt(0)
	v_mfma_f32_32x32x16_bf16 v[128:143], v[8:11], v[156:159], v[128:143]
	v_add_f32_e32 v1, v103, v1
	v_add_f32_e32 v1, v104, v1
	v_add_f32_e32 v1, v105, v1
	v_add_f32_e32 v1, v106, v1
	v_add_f32_e32 v1, v107, v1
	v_add_f32_e32 v1, v108, v1
	v_add_f32_e32 v1, v109, v1
	v_mfma_f32_32x32x16_bf16 v[112:127], v[4:7], v[156:159], v[112:127]
	ds_read_b128 v[4:7], v166 offset:51264
	ds_read_b128 v[8:11], v167 offset:51264
	v_add_f32_e32 v1, v110, v1
	v_add_f32_e32 v1, v111, v1
	v_add_f32_e32 v1, v80, v1
	v_add_f32_e32 v1, v81, v1
	v_add_f32_e32 v1, v82, v1
	v_add_f32_e32 v1, v83, v1
	s_waitcnt lgkmcnt(0)
	v_mfma_f32_32x32x16_bf16 v[128:143], v[8:11], v[152:155], v[128:143]
	v_add_f32_e32 v1, v84, v1
	v_add_f32_e32 v1, v85, v1
	v_add_f32_e32 v1, v86, v1
	v_add_f32_e32 v1, v87, v1
	v_add_f32_e32 v1, v88, v1
	v_add_f32_e32 v1, v89, v1
	v_add_f32_e32 v1, v90, v1
	v_mfma_f32_32x32x16_bf16 v[112:127], v[4:7], v[152:155], v[112:127]
	ds_read_b128 v[4:7], v166 offset:53376
	ds_read_b128 v[8:11], v167 offset:53376
	v_add_f32_e32 v1, v91, v1
	v_add_f32_e32 v1, v92, v1
	v_add_f32_e32 v1, v93, v1
	v_add_f32_e32 v1, v94, v1
	v_add_f32_e32 v1, v95, v1
	v_mov_b32_e32 v2, v1
	s_waitcnt lgkmcnt(0)
	v_mfma_f32_32x32x16_bf16 v[128:143], v[8:11], v[148:151], v[128:143]
	v_permlane32_swap_b32_e32 v1, v2
	v_mfma_f32_32x32x16_bf16 v[112:127], v[4:7], v[148:151], v[112:127]
	ds_read_b128 v[4:7], v166 offset:55488
	ds_read_b128 v[8:11], v167 offset:55488
	v_cvt_pk_bf16_f32 v166, v96, v97
	v_cvt_pk_bf16_f32 v167, v98, v99
	v_cvt_pk_bf16_f32 v168, v100, v101
	v_cvt_pk_bf16_f32 v169, v102, v103
	v_cvt_pk_bf16_f32 v12, v104, v105
	v_cvt_pk_bf16_f32 v13, v106, v107
	s_waitcnt lgkmcnt(0)
	v_mfma_f32_32x32x16_bf16 v[128:143], v[8:11], v[144:147], v[128:143]
	v_cvt_pk_bf16_f32 v14, v108, v109
	v_cvt_pk_bf16_f32 v15, v110, v111
	v_cvt_pk_bf16_f32 v8, v80, v81
	v_cvt_pk_bf16_f32 v9, v82, v83
	v_cvt_pk_bf16_f32 v10, v84, v85
	v_cvt_pk_bf16_f32 v11, v86, v87
	v_mfma_f32_32x32x16_bf16 v[112:127], v[4:7], v[144:147], v[112:127]
	v_cvt_pk_bf16_f32 v4, v88, v89
	v_cvt_pk_bf16_f32 v5, v90, v91
	v_cvt_pk_bf16_f32 v6, v92, v93
	v_cvt_pk_bf16_f32 v7, v94, v95
	v_lshl_add_u32 v162, s69, 14, v215
	ds_read_b64_tr_b16 v[182:183], v162 offset:0
	ds_read_b64_tr_b16 v[184:185], v162 offset:0x800
	ds_read_b64_tr_b16 v[178:179], v162 offset:0x1000
	ds_read_b64_tr_b16 v[180:181], v162 offset:0x1800
	s_add_i32 s54, s64, s45
	ds_read_b64_tr_b16 v[174:175], v162 offset:0x2000
	s_cmp_eq_u32 s54, 4
	ds_read_b64_tr_b16 v[176:177], v162 offset:0x2800
	s_cselect_b64 s[54:55], -1, 0
	ds_read_b64_tr_b16 v[170:171], v162 offset:0x3000
	v_cndmask_b32_e64 v80, 0, 1, s[54:55]
	ds_read_b64_tr_b16 v[172:173], v162 offset:0x3800
	s_add_i32 s98, s70, 2
	s_cmp_le_i32 s98, s31
	s_cbranch_scc0 .Lold_even
	v_max3_f32 v245, v128, v129, v130
	v_max3_f32 v246, v112, v113, v114
	v_max3_f32 v245, v245, v131, v132
	v_max3_f32 v246, v246, v115, v116
	v_max3_f32 v245, v245, v133, v134
	v_max3_f32 v246, v246, v117, v118
	v_max3_f32 v245, v245, v135, v136
	v_max3_f32 v246, v246, v119, v120
	v_max3_f32 v245, v245, v137, v138
	v_max3_f32 v246, v246, v121, v122
	v_max3_f32 v245, v245, v139, v140
	v_max3_f32 v246, v246, v123, v124
	v_max3_f32 v245, v245, v141, v142
	v_max3_f32 v246, v246, v125, v126
	v_max_f32_e32 v245, v245, v143
	v_max_f32_e32 v246, v246, v127
	v_max_f32_e32 v245, v245, v246
	v_mov_b32_e32 v246, v245
	s_nop 1
	v_permlane32_swap_b32_e32 v245, v246
	v_max_f32_e32 v245, v245, v246
	v_cmp_ge_f32_e32 vcc, s68, v245
	s_cmp_eq_u64 vcc, exec
	v_mov_b32_e32 v196, 1.0
	s_cbranch_scc0 .Lf_even_resc

.LBB0_1452:
	v_add_f32_e32 v4, v223, v224
	s_waitcnt vmcnt(0)
	s_add_i32 s54, s67, 1
	v_fmac_f32_e32 v4, v222, v214
	v_add_f32_e32 v214, v1, v2
	s_cmp_lg_u32 s67, 2
	v_fmac_f32_e32 v214, v4, v225
	s_cselect_b32 s55, s54, 0
	s_add_i32 s45, s45, 2
	s_addk_i32 s65, 0x80
	v_lshl_add_u64 v[194:195], v[194:195], 0, s[16:17]
	s_and_b64 vcc, exec, s[52:53]
	s_waitcnt vmcnt(0)
	s_cbranch_vccnz .Lrot10_exit
	s_mov_b32 s54, s44
	s_mov_b32 s69, s67
	s_mov_b32 s44, s55
	v_mov_b32_e32 v222, v196
	s_branch .LBB0_1422
